# 128 of the 704 wg2/wu2 fp8 copy items moved from P4 into P1's idle round (one per idle workgroup, hand-written LDS-free copy), P4 keeps 576
# baseline (speedup 1.0000x reference)
.LBB0_285:
	s_cmpk_lt_u32 s2, 0x80
	s_cbranch_scc1 .Lcp_p1_skip
	s_mov_b64 exec, -1
.Lcp_p1_entry:
	s_load_dwordx2 s[40:41], s[0:1], 0x70
	s_load_dwordx4 s[60:63], s[0:1], 0x78
	v_mbcnt_lo_u32_b32 v194, -1, 0
	v_mbcnt_hi_u32_b32 v194, -1, v194
	s_lshr_b32 s77, s91, 2
	s_lshl_b32 s77, s77, 2
	s_add_i32 s77, s77, s91
	s_lshl_b32 s77, s77, 16
	v_lshrrev_b32_e32 v214, 3, v194
	v_and_b32_e32 v215, 7, v194
	v_mul_u32_u24_e32 v213, 0x58000, v214
	v_lshl_add_u32 v213, v215, 4, v213
	v_lshlrev_b32_e32 v217, 6, v214
	v_lshl_add_u32 v216, v215, 3, v214
	v_lshlrev_b32_e32 v216, 2, v216
	v_lshlrev_b32_e32 v214, 13, v214
	v_lshl_add_u32 v214, v215, 4, v214
	v_add_u32_e32 v215, 0x1000, v214
	v_mov_b32_e32 v210, 0x44800000
	v_mov_b32_e32 v211, 0x43e00000
	v_mov_b32_e32 v212, 0xc3e00000
	s_waitcnt lgkmcnt(0)
	s_add_i32 s44, s2, 448
	s_cmpk_ge_u32 s44, 0x160
	s_cselect_b32 s45, 1, 0
	s_mul_i32 s78, s45, 0x160
	s_sub_i32 s44, s44, s78
	s_mul_i32 s78, s44, 2979
	s_lshr_b32 s78, s78, 16
	s_mul_i32 s69, s78, 22
	s_sub_i32 s69, s44, s69
	s_lshl_b32 s78, s78, 7
	s_cmp_eq_u32 s45, 0
	s_cselect_b32 s20, s60, s62
	s_cselect_b32 s21, s61, s63
	s_mul_i32 s76, s78, 0x5800
	s_lshl_b32 s44, s69, 10
	s_add_i32 s76, s76, s44
	s_lshl_b32 s44, s91, 7
	s_add_i32 s76, s76, s44
	s_add_u32 s20, s20, s76
	s_addc_u32 s21, s21, 0
	s_lshl_b32 s44, s78, 2
	s_add_u32 s34, s40, s44
	s_addc_u32 s35, s41, 0
	s_lshl_b32 s44, s69, 20
	s_lshl_b32 s45, s45, 18
	s_add_i32 s44, s44, s45
	s_add_i32 s44, s44, s78
	s_add_i32 s44, s44, s77
	s_add_u32 s26, s50, s44
	s_addc_u32 s27, s51, 0
	s_add_u32 s26, s26, 0x6300000
	s_addc_u32 s27, s27, 0
	global_load_dwordx4 v[64:67], v217, s[34:35] offset:0
	global_load_dwordx4 v[68:71], v217, s[34:35] offset:16
	global_load_dwordx4 v[72:75], v217, s[34:35] offset:32
	global_load_dwordx4 v[76:79], v217, s[34:35] offset:48
	global_load_dwordx4 v[0:3], v213, s[20:21] nt
	s_add_u32 s20, s20, 0x5800
	s_addc_u32 s21, s21, 0
	global_load_dwordx4 v[4:7], v213, s[20:21] nt
	s_add_u32 s20, s20, 0x5800
	s_addc_u32 s21, s21, 0
	global_load_dwordx4 v[8:11], v213, s[20:21] nt
	s_add_u32 s20, s20, 0x5800
	s_addc_u32 s21, s21, 0
	global_load_dwordx4 v[12:15], v213, s[20:21] nt
	s_add_u32 s20, s20, 0x5800
	s_addc_u32 s21, s21, 0
	global_load_dwordx4 v[16:19], v213, s[20:21] nt
	s_add_u32 s20, s20, 0x5800
	s_addc_u32 s21, s21, 0
	global_load_dwordx4 v[20:23], v213, s[20:21] nt
	s_add_u32 s20, s20, 0x5800
	s_addc_u32 s21, s21, 0
	global_load_dwordx4 v[24:27], v213, s[20:21] nt
	s_add_u32 s20, s20, 0x5800
	s_addc_u32 s21, s21, 0
	global_load_dwordx4 v[28:31], v213, s[20:21] nt
	s_add_u32 s20, s20, 0x5800
	s_addc_u32 s21, s21, 0
	global_load_dwordx4 v[32:35], v213, s[20:21] nt
	s_add_u32 s20, s20, 0x5800
	s_addc_u32 s21, s21, 0
	global_load_dwordx4 v[36:39], v213, s[20:21] nt
	s_add_u32 s20, s20, 0x5800
	s_addc_u32 s21, s21, 0
	global_load_dwordx4 v[40:43], v213, s[20:21] nt
	s_add_u32 s20, s20, 0x5800
	s_addc_u32 s21, s21, 0
	global_load_dwordx4 v[44:47], v213, s[20:21] nt
	s_add_u32 s20, s20, 0x5800
	s_addc_u32 s21, s21, 0
	global_load_dwordx4 v[48:51], v213, s[20:21] nt
	s_add_u32 s20, s20, 0x5800
	s_addc_u32 s21, s21, 0
	global_load_dwordx4 v[52:55], v213, s[20:21] nt
	s_add_u32 s20, s20, 0x5800
	s_addc_u32 s21, s21, 0
	global_load_dwordx4 v[56:59], v213, s[20:21] nt
	s_add_u32 s20, s20, 0x5800
	s_addc_u32 s21, s21, 0
	global_load_dwordx4 v[60:63], v213, s[20:21] nt
	s_waitcnt vmcnt(0)
	v_mul_f32_e32 v64, v64, v210
	v_mul_f32_e32 v65, v65, v210
	v_mul_f32_e32 v66, v66, v210
	v_mul_f32_e32 v67, v67, v210
	v_mul_f32_e32 v68, v68, v210
	v_mul_f32_e32 v69, v69, v210
	v_mul_f32_e32 v70, v70, v210
	v_mul_f32_e32 v71, v71, v210
	v_mul_f32_e32 v72, v72, v210
	v_mul_f32_e32 v73, v73, v210
	v_mul_f32_e32 v74, v74, v210
	v_mul_f32_e32 v75, v75, v210
	v_mul_f32_e32 v76, v76, v210
	v_mul_f32_e32 v77, v77, v210
	v_mul_f32_e32 v78, v78, v210
	v_mul_f32_e32 v79, v79, v210
	v_pk_mul_f32 v[0:1], v[0:1], v[64:65] op_sel_hi:[1,0]
	v_pk_mul_f32 v[2:3], v[2:3], v[64:65] op_sel_hi:[1,0]
	v_pk_mul_f32 v[4:5], v[4:5], v[64:65] op_sel:[0,1] op_sel_hi:[1,1]
	v_pk_mul_f32 v[6:7], v[6:7], v[64:65] op_sel:[0,1] op_sel_hi:[1,1]
	v_pk_mul_f32 v[8:9], v[8:9], v[66:67] op_sel_hi:[1,0]
	v_pk_mul_f32 v[10:11], v[10:11], v[66:67] op_sel_hi:[1,0]
	v_pk_mul_f32 v[12:13], v[12:13], v[66:67] op_sel:[0,1] op_sel_hi:[1,1]
	v_pk_mul_f32 v[14:15], v[14:15], v[66:67] op_sel:[0,1] op_sel_hi:[1,1]
	v_pk_mul_f32 v[16:17], v[16:17], v[68:69] op_sel_hi:[1,0]
	v_pk_mul_f32 v[18:19], v[18:19], v[68:69] op_sel_hi:[1,0]
	v_pk_mul_f32 v[20:21], v[20:21], v[68:69] op_sel:[0,1] op_sel_hi:[1,1]
	v_pk_mul_f32 v[22:23], v[22:23], v[68:69] op_sel:[0,1] op_sel_hi:[1,1]
	v_pk_mul_f32 v[24:25], v[24:25], v[70:71] op_sel_hi:[1,0]
	v_pk_mul_f32 v[26:27], v[26:27], v[70:71] op_sel_hi:[1,0]
	v_pk_mul_f32 v[28:29], v[28:29], v[70:71] op_sel:[0,1] op_sel_hi:[1,1]
	v_pk_mul_f32 v[30:31], v[30:31], v[70:71] op_sel:[0,1] op_sel_hi:[1,1]
	v_pk_mul_f32 v[32:33], v[32:33], v[72:73] op_sel_hi:[1,0]
	v_pk_mul_f32 v[34:35], v[34:35], v[72:73] op_sel_hi:[1,0]
	v_pk_mul_f32 v[36:37], v[36:37], v[72:73] op_sel:[0,1] op_sel_hi:[1,1]
	v_pk_mul_f32 v[38:39], v[38:39], v[72:73] op_sel:[0,1] op_sel_hi:[1,1]
	v_pk_mul_f32 v[40:41], v[40:41], v[74:75] op_sel_hi:[1,0]
	v_pk_mul_f32 v[42:43], v[42:43], v[74:75] op_sel_hi:[1,0]
	v_pk_mul_f32 v[44:45], v[44:45], v[74:75] op_sel:[0,1] op_sel_hi:[1,1]
	v_pk_mul_f32 v[46:47], v[46:47], v[74:75] op_sel:[0,1] op_sel_hi:[1,1]
	v_pk_mul_f32 v[48:49], v[48:49], v[76:77] op_sel_hi:[1,0]
	v_pk_mul_f32 v[50:51], v[50:51], v[76:77] op_sel_hi:[1,0]
	v_pk_mul_f32 v[52:53], v[52:53], v[76:77] op_sel:[0,1] op_sel_hi:[1,1]
	v_pk_mul_f32 v[54:55], v[54:55], v[76:77] op_sel:[0,1] op_sel_hi:[1,1]
	v_pk_mul_f32 v[56:57], v[56:57], v[78:79] op_sel_hi:[1,0]
	v_pk_mul_f32 v[58:59], v[58:59], v[78:79] op_sel_hi:[1,0]
	v_pk_mul_f32 v[60:61], v[60:61], v[78:79] op_sel:[0,1] op_sel_hi:[1,1]
	v_pk_mul_f32 v[62:63], v[62:63], v[78:79] op_sel:[0,1] op_sel_hi:[1,1]
	v_med3_f32 v0, v0, v212, v211
	v_med3_f32 v1, v1, v212, v211
	v_med3_f32 v2, v2, v212, v211
	v_med3_f32 v3, v3, v212, v211
	v_med3_f32 v4, v4, v212, v211
	v_med3_f32 v5, v5, v212, v211
	v_med3_f32 v6, v6, v212, v211
	v_med3_f32 v7, v7, v212, v211
	v_med3_f32 v8, v8, v212, v211
	v_med3_f32 v9, v9, v212, v211
	v_med3_f32 v10, v10, v212, v211
	v_med3_f32 v11, v11, v212, v211
	v_med3_f32 v12, v12, v212, v211
	v_med3_f32 v13, v13, v212, v211
	v_med3_f32 v14, v14, v212, v211
	v_med3_f32 v15, v15, v212, v211
	v_med3_f32 v16, v16, v212, v211
	v_med3_f32 v17, v17, v212, v211
	v_med3_f32 v18, v18, v212, v211
	v_med3_f32 v19, v19, v212, v211
	v_med3_f32 v20, v20, v212, v211
	v_med3_f32 v21, v21, v212, v211
	v_med3_f32 v22, v22, v212, v211
	v_med3_f32 v23, v23, v212, v211
	v_med3_f32 v24, v24, v212, v211
	v_med3_f32 v25, v25, v212, v211
	v_med3_f32 v26, v26, v212, v211
	v_med3_f32 v27, v27, v212, v211
	v_med3_f32 v28, v28, v212, v211
	v_med3_f32 v29, v29, v212, v211
	v_med3_f32 v30, v30, v212, v211
	v_med3_f32 v31, v31, v212, v211
	v_med3_f32 v32, v32, v212, v211
	v_med3_f32 v33, v33, v212, v211
	v_med3_f32 v34, v34, v212, v211
	v_med3_f32 v35, v35, v212, v211
	v_med3_f32 v36, v36, v212, v211
	v_med3_f32 v37, v37, v212, v211
	v_med3_f32 v38, v38, v212, v211
	v_med3_f32 v39, v39, v212, v211
	v_med3_f32 v40, v40, v212, v211
	v_med3_f32 v41, v41, v212, v211
	v_med3_f32 v42, v42, v212, v211
	v_med3_f32 v43, v43, v212, v211
	v_med3_f32 v44, v44, v212, v211
	v_med3_f32 v45, v45, v212, v211
	v_med3_f32 v46, v46, v212, v211
	v_med3_f32 v47, v47, v212, v211
	v_med3_f32 v48, v48, v212, v211
	v_med3_f32 v49, v49, v212, v211
	v_med3_f32 v50, v50, v212, v211
	v_med3_f32 v51, v51, v212, v211
	v_med3_f32 v52, v52, v212, v211
	v_med3_f32 v53, v53, v212, v211
	v_med3_f32 v54, v54, v212, v211
	v_med3_f32 v55, v55, v212, v211
	v_med3_f32 v56, v56, v212, v211
	v_med3_f32 v57, v57, v212, v211
	v_med3_f32 v58, v58, v212, v211
	v_med3_f32 v59, v59, v212, v211
	v_med3_f32 v60, v60, v212, v211
	v_med3_f32 v61, v61, v212, v211
	v_med3_f32 v62, v62, v212, v211
	v_med3_f32 v63, v63, v212, v211
	v_cvt_pk_fp8_f32 v160, v0, v4
	v_cvt_pk_fp8_f32 v161, v16, v20
	v_cvt_pk_fp8_f32 v162, v32, v36
	v_cvt_pk_fp8_f32 v163, v48, v52
	v_cvt_pk_fp8_f32 v164, v1, v5
	v_cvt_pk_fp8_f32 v165, v17, v21
	v_cvt_pk_fp8_f32 v166, v33, v37
	v_cvt_pk_fp8_f32 v167, v49, v53
	v_cvt_pk_fp8_f32 v168, v2, v6
	v_cvt_pk_fp8_f32 v169, v18, v22
	v_cvt_pk_fp8_f32 v170, v34, v38
	v_cvt_pk_fp8_f32 v171, v50, v54
	v_cvt_pk_fp8_f32 v172, v3, v7
	v_cvt_pk_fp8_f32 v173, v19, v23
	v_cvt_pk_fp8_f32 v174, v35, v39
	v_cvt_pk_fp8_f32 v175, v51, v55
	v_cvt_pk_fp8_f32 v160, v8, v12 op_sel:[0,0,1]
	v_cvt_pk_fp8_f32 v161, v24, v28 op_sel:[0,0,1]
	v_cvt_pk_fp8_f32 v162, v40, v44 op_sel:[0,0,1]
	v_cvt_pk_fp8_f32 v163, v56, v60 op_sel:[0,0,1]
	v_cvt_pk_fp8_f32 v164, v9, v13 op_sel:[0,0,1]
	v_cvt_pk_fp8_f32 v165, v25, v29 op_sel:[0,0,1]
	v_cvt_pk_fp8_f32 v166, v41, v45 op_sel:[0,0,1]
	v_cvt_pk_fp8_f32 v167, v57, v61 op_sel:[0,0,1]
	v_cvt_pk_fp8_f32 v168, v10, v14 op_sel:[0,0,1]
	v_cvt_pk_fp8_f32 v169, v26, v30 op_sel:[0,0,1]
	v_cvt_pk_fp8_f32 v170, v42, v46 op_sel:[0,0,1]
	v_cvt_pk_fp8_f32 v171, v58, v62 op_sel:[0,0,1]
	v_cvt_pk_fp8_f32 v172, v11, v15 op_sel:[0,0,1]
	v_cvt_pk_fp8_f32 v173, v27, v31 op_sel:[0,0,1]
	v_cvt_pk_fp8_f32 v174, v43, v47 op_sel:[0,0,1]
	v_cvt_pk_fp8_f32 v175, v59, v63 op_sel:[0,0,1]
	s_nop 0
	ds_bpermute_b32 v194, v216, v160
	ds_bpermute_b32 v195, v216, v161
	ds_bpermute_b32 v196, v216, v162
	ds_bpermute_b32 v197, v216, v163
	ds_bpermute_b32 v198, v216, v164
	ds_bpermute_b32 v199, v216, v165
	ds_bpermute_b32 v200, v216, v166
	ds_bpermute_b32 v201, v216, v167
	ds_bpermute_b32 v202, v216, v168
	ds_bpermute_b32 v203, v216, v169
	ds_bpermute_b32 v204, v216, v170
	ds_bpermute_b32 v205, v216, v171
	ds_bpermute_b32 v206, v216, v172
	ds_bpermute_b32 v207, v216, v173
	ds_bpermute_b32 v208, v216, v174
	ds_bpermute_b32 v209, v216, v175
	s_waitcnt lgkmcnt(0)
	global_store_dwordx4 v214, v[194:197], s[26:27]
	global_store_dwordx4 v214, v[198:201], s[26:27] offset:2048
	global_store_dwordx4 v215, v[202:205], s[26:27]
	global_store_dwordx4 v215, v[206:209], s[26:27] offset:2048
.Lcp_p1_done:
.Lcp_p1_skip:
	s_waitcnt vmcnt(15)
	v_cndmask_b32_e64 v0, 0, 1, s[64:65]
	v_cmp_ne_u32_e64 s[42:43], 1, v0
	s_andn2_b64 vcc, exec, s[64:65]
	s_mov_b64 s[8:9], 0
	s_cbranch_vccnz .LBB0_287
	v_mbcnt_lo_u32_b32 v0, -1, 0
	v_mbcnt_hi_u32_b32 v0, -1, v0
	s_nop 0
	v_cmp_eq_u32_e32 vcc, 0, v0
	s_and_b64 s[8:9], vcc, exec

.Lp4_copy_entry:
.Lcp_p4_entry:
	s_load_dwordx2 s[40:41], s[0:1], 0x70
	s_load_dwordx4 s[60:63], s[0:1], 0x78
	v_mbcnt_lo_u32_b32 v194, -1, 0
	v_mbcnt_hi_u32_b32 v194, -1, v194
	s_lshr_b32 s77, s91, 2
	s_lshl_b32 s77, s77, 2
	s_add_i32 s77, s77, s91
	s_lshl_b32 s77, s77, 16
	v_lshrrev_b32_e32 v214, 3, v194
	v_and_b32_e32 v215, 7, v194
	v_mul_u32_u24_e32 v213, 0x58000, v214
	v_lshl_add_u32 v213, v215, 4, v213
	v_lshlrev_b32_e32 v217, 6, v214
	v_lshl_add_u32 v216, v215, 3, v214
	v_lshlrev_b32_e32 v216, 2, v216
	v_lshlrev_b32_e32 v214, 13, v214
	v_lshl_add_u32 v214, v215, 4, v214
	v_add_u32_e32 v215, 0x1000, v214
	v_mov_b32_e32 v210, 0x44800000
	v_mov_b32_e32 v211, 0x43e00000
	v_mov_b32_e32 v212, 0xc3e00000
	s_waitcnt lgkmcnt(0)
	s_mov_b32 s44, s2
	s_cmpk_ge_u32 s44, 0x160
	s_cselect_b32 s45, 1, 0
	s_mul_i32 s78, s45, 0x160
	s_sub_i32 s44, s44, s78
	s_mul_i32 s78, s44, 2979
	s_lshr_b32 s78, s78, 16
	s_mul_i32 s69, s78, 22
	s_sub_i32 s69, s44, s69
	s_lshl_b32 s78, s78, 7
	s_cmp_eq_u32 s45, 0
	s_cselect_b32 s20, s60, s62
	s_cselect_b32 s21, s61, s63
	s_mul_i32 s76, s78, 0x5800
	s_lshl_b32 s44, s69, 10
	s_add_i32 s76, s76, s44
	s_lshl_b32 s44, s91, 7
	s_add_i32 s76, s76, s44
	s_add_u32 s20, s20, s76
	s_addc_u32 s21, s21, 0
	s_lshl_b32 s44, s78, 2
	s_add_u32 s34, s40, s44
	s_addc_u32 s35, s41, 0
	s_lshl_b32 s44, s69, 20
	s_lshl_b32 s45, s45, 18
	s_add_i32 s44, s44, s45
	s_add_i32 s44, s44, s78
	s_add_i32 s44, s44, s77
	s_add_u32 s26, s50, s44
	s_addc_u32 s27, s51, 0
	s_add_u32 s26, s26, 0x6300000
	s_addc_u32 s27, s27, 0
	global_load_dwordx4 v[64:67], v217, s[34:35] offset:0
	global_load_dwordx4 v[68:71], v217, s[34:35] offset:16
	global_load_dwordx4 v[72:75], v217, s[34:35] offset:32
	global_load_dwordx4 v[76:79], v217, s[34:35] offset:48
	global_load_dwordx4 v[0:3], v213, s[20:21] nt
	s_add_u32 s20, s20, 0x5800
	s_addc_u32 s21, s21, 0
	global_load_dwordx4 v[4:7], v213, s[20:21] nt
	s_add_u32 s20, s20, 0x5800
	s_addc_u32 s21, s21, 0
	global_load_dwordx4 v[8:11], v213, s[20:21] nt
	s_add_u32 s20, s20, 0x5800
	s_addc_u32 s21, s21, 0
	global_load_dwordx4 v[12:15], v213, s[20:21] nt
	s_add_u32 s20, s20, 0x5800
	s_addc_u32 s21, s21, 0
	global_load_dwordx4 v[16:19], v213, s[20:21] nt
	s_add_u32 s20, s20, 0x5800
	s_addc_u32 s21, s21, 0
	global_load_dwordx4 v[20:23], v213, s[20:21] nt
	s_add_u32 s20, s20, 0x5800
	s_addc_u32 s21, s21, 0
	global_load_dwordx4 v[24:27], v213, s[20:21] nt
	s_add_u32 s20, s20, 0x5800
	s_addc_u32 s21, s21, 0
	global_load_dwordx4 v[28:31], v213, s[20:21] nt
	s_add_u32 s20, s20, 0x5800
	s_addc_u32 s21, s21, 0
	global_load_dwordx4 v[32:35], v213, s[20:21] nt
	s_add_u32 s20, s20, 0x5800
	s_addc_u32 s21, s21, 0
	global_load_dwordx4 v[36:39], v213, s[20:21] nt
	s_add_u32 s20, s20, 0x5800
	s_addc_u32 s21, s21, 0
	global_load_dwordx4 v[40:43], v213, s[20:21] nt
	s_add_u32 s20, s20, 0x5800
	s_addc_u32 s21, s21, 0
	global_load_dwordx4 v[44:47], v213, s[20:21] nt
	s_add_u32 s20, s20, 0x5800
	s_addc_u32 s21, s21, 0
	global_load_dwordx4 v[48:51], v213, s[20:21] nt
	s_add_u32 s20, s20, 0x5800
	s_addc_u32 s21, s21, 0
	global_load_dwordx4 v[52:55], v213, s[20:21] nt
	s_add_u32 s20, s20, 0x5800
	s_addc_u32 s21, s21, 0
	global_load_dwordx4 v[56:59], v213, s[20:21] nt
	s_add_u32 s20, s20, 0x5800
	s_addc_u32 s21, s21, 0
	global_load_dwordx4 v[60:63], v213, s[20:21] nt
	s_add_i32 s44, s2, 256
	s_cmpk_ge_u32 s44, 0x160
	s_cselect_b32 s45, 1, 0
	s_mul_i32 s78, s45, 0x160
	s_sub_i32 s44, s44, s78
	s_mul_i32 s78, s44, 2979
	s_lshr_b32 s78, s78, 16
	s_mul_i32 s69, s78, 22
	s_sub_i32 s69, s44, s69
	s_lshl_b32 s78, s78, 7
	s_cmp_eq_u32 s45, 0
	s_cselect_b32 s22, s60, s62
	s_cselect_b32 s23, s61, s63
	s_mul_i32 s76, s78, 0x5800
	s_lshl_b32 s44, s69, 10
	s_add_i32 s76, s76, s44
	s_lshl_b32 s44, s91, 7
	s_add_i32 s76, s76, s44
	s_add_u32 s22, s22, s76
	s_addc_u32 s23, s23, 0
	s_lshl_b32 s44, s78, 2
	s_add_u32 s36, s40, s44
	s_addc_u32 s37, s41, 0
	s_lshl_b32 s44, s69, 20
	s_lshl_b32 s45, s45, 18
	s_add_i32 s44, s44, s45
	s_add_i32 s44, s44, s78
	s_add_i32 s44, s44, s77
	s_add_u32 s28, s50, s44
	s_addc_u32 s29, s51, 0
	s_add_u32 s28, s28, 0x6300000
	s_addc_u32 s29, s29, 0
	global_load_dwordx4 v[144:147], v217, s[36:37] offset:0
	global_load_dwordx4 v[148:151], v217, s[36:37] offset:16
	global_load_dwordx4 v[152:155], v217, s[36:37] offset:32
	global_load_dwordx4 v[156:159], v217, s[36:37] offset:48
	global_load_dwordx4 v[80:83], v213, s[22:23] nt
	s_add_u32 s22, s22, 0x5800
	s_addc_u32 s23, s23, 0
	global_load_dwordx4 v[84:87], v213, s[22:23] nt
	s_add_u32 s22, s22, 0x5800
	s_addc_u32 s23, s23, 0
	global_load_dwordx4 v[88:91], v213, s[22:23] nt
	s_add_u32 s22, s22, 0x5800
	s_addc_u32 s23, s23, 0
	global_load_dwordx4 v[92:95], v213, s[22:23] nt
	s_add_u32 s22, s22, 0x5800
	s_addc_u32 s23, s23, 0
	global_load_dwordx4 v[96:99], v213, s[22:23] nt
	s_add_u32 s22, s22, 0x5800
	s_addc_u32 s23, s23, 0
	global_load_dwordx4 v[100:103], v213, s[22:23] nt
	s_add_u32 s22, s22, 0x5800
	s_addc_u32 s23, s23, 0
	global_load_dwordx4 v[104:107], v213, s[22:23] nt
	s_add_u32 s22, s22, 0x5800
	s_addc_u32 s23, s23, 0
	global_load_dwordx4 v[108:111], v213, s[22:23] nt
	s_add_u32 s22, s22, 0x5800
	s_addc_u32 s23, s23, 0
	global_load_dwordx4 v[112:115], v213, s[22:23] nt
	s_add_u32 s22, s22, 0x5800
	s_addc_u32 s23, s23, 0
	global_load_dwordx4 v[116:119], v213, s[22:23] nt
	s_add_u32 s22, s22, 0x5800
	s_addc_u32 s23, s23, 0
	global_load_dwordx4 v[120:123], v213, s[22:23] nt
	s_add_u32 s22, s22, 0x5800
	s_addc_u32 s23, s23, 0
	global_load_dwordx4 v[124:127], v213, s[22:23] nt
	s_add_u32 s22, s22, 0x5800
	s_addc_u32 s23, s23, 0
	global_load_dwordx4 v[128:131], v213, s[22:23] nt
	s_add_u32 s22, s22, 0x5800
	s_addc_u32 s23, s23, 0
	global_load_dwordx4 v[132:135], v213, s[22:23] nt
	s_add_u32 s22, s22, 0x5800
	s_addc_u32 s23, s23, 0
	global_load_dwordx4 v[136:139], v213, s[22:23] nt
	s_add_u32 s22, s22, 0x5800
	s_addc_u32 s23, s23, 0
	global_load_dwordx4 v[140:143], v213, s[22:23] nt
	s_waitcnt vmcnt(20)
	v_mul_f32_e32 v64, v64, v210
	v_mul_f32_e32 v65, v65, v210
	v_mul_f32_e32 v66, v66, v210
	v_mul_f32_e32 v67, v67, v210
	v_mul_f32_e32 v68, v68, v210
	v_mul_f32_e32 v69, v69, v210
	v_mul_f32_e32 v70, v70, v210
	v_mul_f32_e32 v71, v71, v210
	v_mul_f32_e32 v72, v72, v210
	v_mul_f32_e32 v73, v73, v210
	v_mul_f32_e32 v74, v74, v210
	v_mul_f32_e32 v75, v75, v210
	v_mul_f32_e32 v76, v76, v210
	v_mul_f32_e32 v77, v77, v210
	v_mul_f32_e32 v78, v78, v210
	v_mul_f32_e32 v79, v79, v210
	v_pk_mul_f32 v[0:1], v[0:1], v[64:65] op_sel_hi:[1,0]
	v_pk_mul_f32 v[2:3], v[2:3], v[64:65] op_sel_hi:[1,0]
	v_pk_mul_f32 v[4:5], v[4:5], v[64:65] op_sel:[0,1] op_sel_hi:[1,1]
	v_pk_mul_f32 v[6:7], v[6:7], v[64:65] op_sel:[0,1] op_sel_hi:[1,1]
	v_pk_mul_f32 v[8:9], v[8:9], v[66:67] op_sel_hi:[1,0]
	v_pk_mul_f32 v[10:11], v[10:11], v[66:67] op_sel_hi:[1,0]
	v_pk_mul_f32 v[12:13], v[12:13], v[66:67] op_sel:[0,1] op_sel_hi:[1,1]
	v_pk_mul_f32 v[14:15], v[14:15], v[66:67] op_sel:[0,1] op_sel_hi:[1,1]
	v_pk_mul_f32 v[16:17], v[16:17], v[68:69] op_sel_hi:[1,0]
	v_pk_mul_f32 v[18:19], v[18:19], v[68:69] op_sel_hi:[1,0]
	v_pk_mul_f32 v[20:21], v[20:21], v[68:69] op_sel:[0,1] op_sel_hi:[1,1]
	v_pk_mul_f32 v[22:23], v[22:23], v[68:69] op_sel:[0,1] op_sel_hi:[1,1]
	v_pk_mul_f32 v[24:25], v[24:25], v[70:71] op_sel_hi:[1,0]
	v_pk_mul_f32 v[26:27], v[26:27], v[70:71] op_sel_hi:[1,0]
	v_pk_mul_f32 v[28:29], v[28:29], v[70:71] op_sel:[0,1] op_sel_hi:[1,1]
	v_pk_mul_f32 v[30:31], v[30:31], v[70:71] op_sel:[0,1] op_sel_hi:[1,1]
	v_pk_mul_f32 v[32:33], v[32:33], v[72:73] op_sel_hi:[1,0]
	v_pk_mul_f32 v[34:35], v[34:35], v[72:73] op_sel_hi:[1,0]
	v_pk_mul_f32 v[36:37], v[36:37], v[72:73] op_sel:[0,1] op_sel_hi:[1,1]
	v_pk_mul_f32 v[38:39], v[38:39], v[72:73] op_sel:[0,1] op_sel_hi:[1,1]
	v_pk_mul_f32 v[40:41], v[40:41], v[74:75] op_sel_hi:[1,0]
	v_pk_mul_f32 v[42:43], v[42:43], v[74:75] op_sel_hi:[1,0]
	v_pk_mul_f32 v[44:45], v[44:45], v[74:75] op_sel:[0,1] op_sel_hi:[1,1]
	v_pk_mul_f32 v[46:47], v[46:47], v[74:75] op_sel:[0,1] op_sel_hi:[1,1]
	v_pk_mul_f32 v[48:49], v[48:49], v[76:77] op_sel_hi:[1,0]
	v_pk_mul_f32 v[50:51], v[50:51], v[76:77] op_sel_hi:[1,0]
	v_pk_mul_f32 v[52:53], v[52:53], v[76:77] op_sel:[0,1] op_sel_hi:[1,1]
	v_pk_mul_f32 v[54:55], v[54:55], v[76:77] op_sel:[0,1] op_sel_hi:[1,1]
	v_pk_mul_f32 v[56:57], v[56:57], v[78:79] op_sel_hi:[1,0]
	v_pk_mul_f32 v[58:59], v[58:59], v[78:79] op_sel_hi:[1,0]
	v_pk_mul_f32 v[60:61], v[60:61], v[78:79] op_sel:[0,1] op_sel_hi:[1,1]
	v_pk_mul_f32 v[62:63], v[62:63], v[78:79] op_sel:[0,1] op_sel_hi:[1,1]
	v_med3_f32 v0, v0, v212, v211
	v_med3_f32 v1, v1, v212, v211
	v_med3_f32 v2, v2, v212, v211
	v_med3_f32 v3, v3, v212, v211
	v_med3_f32 v4, v4, v212, v211
	v_med3_f32 v5, v5, v212, v211
	v_med3_f32 v6, v6, v212, v211
	v_med3_f32 v7, v7, v212, v211
	v_med3_f32 v8, v8, v212, v211
	v_med3_f32 v9, v9, v212, v211
	v_med3_f32 v10, v10, v212, v211
	v_med3_f32 v11, v11, v212, v211
	v_med3_f32 v12, v12, v212, v211
	v_med3_f32 v13, v13, v212, v211
	v_med3_f32 v14, v14, v212, v211
	v_med3_f32 v15, v15, v212, v211
	v_med3_f32 v16, v16, v212, v211
	v_med3_f32 v17, v17, v212, v211
	v_med3_f32 v18, v18, v212, v211
	v_med3_f32 v19, v19, v212, v211
	v_med3_f32 v20, v20, v212, v211
	v_med3_f32 v21, v21, v212, v211
	v_med3_f32 v22, v22, v212, v211
	v_med3_f32 v23, v23, v212, v211
	v_med3_f32 v24, v24, v212, v211
	v_med3_f32 v25, v25, v212, v211
	v_med3_f32 v26, v26, v212, v211
	v_med3_f32 v27, v27, v212, v211
	v_med3_f32 v28, v28, v212, v211
	v_med3_f32 v29, v29, v212, v211
	v_med3_f32 v30, v30, v212, v211
	v_med3_f32 v31, v31, v212, v211
	v_med3_f32 v32, v32, v212, v211
	v_med3_f32 v33, v33, v212, v211
	v_med3_f32 v34, v34, v212, v211
	v_med3_f32 v35, v35, v212, v211
	v_med3_f32 v36, v36, v212, v211
	v_med3_f32 v37, v37, v212, v211
	v_med3_f32 v38, v38, v212, v211
	v_med3_f32 v39, v39, v212, v211
	v_med3_f32 v40, v40, v212, v211
	v_med3_f32 v41, v41, v212, v211
	v_med3_f32 v42, v42, v212, v211
	v_med3_f32 v43, v43, v212, v211
	v_med3_f32 v44, v44, v212, v211
	v_med3_f32 v45, v45, v212, v211
	v_med3_f32 v46, v46, v212, v211
	v_med3_f32 v47, v47, v212, v211
	v_med3_f32 v48, v48, v212, v211
	v_med3_f32 v49, v49, v212, v211
	v_med3_f32 v50, v50, v212, v211
	v_med3_f32 v51, v51, v212, v211
	v_med3_f32 v52, v52, v212, v211
	v_med3_f32 v53, v53, v212, v211
	v_med3_f32 v54, v54, v212, v211
	v_med3_f32 v55, v55, v212, v211
	v_med3_f32 v56, v56, v212, v211
	v_med3_f32 v57, v57, v212, v211
	v_med3_f32 v58, v58, v212, v211
	v_med3_f32 v59, v59, v212, v211
	v_med3_f32 v60, v60, v212, v211
	v_med3_f32 v61, v61, v212, v211
	v_med3_f32 v62, v62, v212, v211
	v_med3_f32 v63, v63, v212, v211
	v_cvt_pk_fp8_f32 v160, v0, v4
	v_cvt_pk_fp8_f32 v161, v16, v20
	v_cvt_pk_fp8_f32 v162, v32, v36
	v_cvt_pk_fp8_f32 v163, v48, v52
	v_cvt_pk_fp8_f32 v164, v1, v5
	v_cvt_pk_fp8_f32 v165, v17, v21
	v_cvt_pk_fp8_f32 v166, v33, v37
	v_cvt_pk_fp8_f32 v167, v49, v53
	v_cvt_pk_fp8_f32 v168, v2, v6
	v_cvt_pk_fp8_f32 v169, v18, v22
	v_cvt_pk_fp8_f32 v170, v34, v38
	v_cvt_pk_fp8_f32 v171, v50, v54
	v_cvt_pk_fp8_f32 v172, v3, v7
	v_cvt_pk_fp8_f32 v173, v19, v23
	v_cvt_pk_fp8_f32 v174, v35, v39
	v_cvt_pk_fp8_f32 v175, v51, v55
	v_cvt_pk_fp8_f32 v160, v8, v12 op_sel:[0,0,1]
	v_cvt_pk_fp8_f32 v161, v24, v28 op_sel:[0,0,1]
	v_cvt_pk_fp8_f32 v162, v40, v44 op_sel:[0,0,1]
	v_cvt_pk_fp8_f32 v163, v56, v60 op_sel:[0,0,1]
	v_cvt_pk_fp8_f32 v164, v9, v13 op_sel:[0,0,1]
	v_cvt_pk_fp8_f32 v165, v25, v29 op_sel:[0,0,1]
	v_cvt_pk_fp8_f32 v166, v41, v45 op_sel:[0,0,1]
	v_cvt_pk_fp8_f32 v167, v57, v61 op_sel:[0,0,1]
	v_cvt_pk_fp8_f32 v168, v10, v14 op_sel:[0,0,1]
	v_cvt_pk_fp8_f32 v169, v26, v30 op_sel:[0,0,1]
	v_cvt_pk_fp8_f32 v170, v42, v46 op_sel:[0,0,1]
	v_cvt_pk_fp8_f32 v171, v58, v62 op_sel:[0,0,1]
	v_cvt_pk_fp8_f32 v172, v11, v15 op_sel:[0,0,1]
	v_cvt_pk_fp8_f32 v173, v27, v31 op_sel:[0,0,1]
	v_cvt_pk_fp8_f32 v174, v43, v47 op_sel:[0,0,1]
	v_cvt_pk_fp8_f32 v175, v59, v63 op_sel:[0,0,1]
	s_nop 0
	ds_bpermute_b32 v194, v216, v160
	ds_bpermute_b32 v195, v216, v161
	ds_bpermute_b32 v196, v216, v162
	ds_bpermute_b32 v197, v216, v163
	ds_bpermute_b32 v198, v216, v164
	ds_bpermute_b32 v199, v216, v165
	ds_bpermute_b32 v200, v216, v166
	ds_bpermute_b32 v201, v216, v167
	ds_bpermute_b32 v202, v216, v168
	ds_bpermute_b32 v203, v216, v169
	ds_bpermute_b32 v204, v216, v170
	ds_bpermute_b32 v205, v216, v171
	ds_bpermute_b32 v206, v216, v172
	ds_bpermute_b32 v207, v216, v173
	ds_bpermute_b32 v208, v216, v174
	ds_bpermute_b32 v209, v216, v175
	s_waitcnt lgkmcnt(0)
	global_store_dwordx4 v214, v[194:197], s[26:27]
	global_store_dwordx4 v214, v[198:201], s[26:27] offset:2048
	global_store_dwordx4 v215, v[202:205], s[26:27]
	global_store_dwordx4 v215, v[206:209], s[26:27] offset:2048
	s_cmpk_lt_u32 s2, 0x40
	s_cbranch_scc0 .Lcp_p4_two
	s_add_i32 s44, s2, 512
	s_cmpk_ge_u32 s44, 0x160
	s_cselect_b32 s45, 1, 0
	s_mul_i32 s78, s45, 0x160
	s_sub_i32 s44, s44, s78
	s_mul_i32 s78, s44, 2979
	s_lshr_b32 s78, s78, 16
	s_mul_i32 s69, s78, 22
	s_sub_i32 s69, s44, s69
	s_lshl_b32 s78, s78, 7
	s_cmp_eq_u32 s45, 0
	s_cselect_b32 s20, s60, s62
	s_cselect_b32 s21, s61, s63
	s_mul_i32 s76, s78, 0x5800
	s_lshl_b32 s44, s69, 10
	s_add_i32 s76, s76, s44
	s_lshl_b32 s44, s91, 7
	s_add_i32 s76, s76, s44
	s_add_u32 s20, s20, s76
	s_addc_u32 s21, s21, 0
	s_lshl_b32 s44, s78, 2
	s_add_u32 s34, s40, s44
	s_addc_u32 s35, s41, 0
	s_lshl_b32 s44, s69, 20
	s_lshl_b32 s45, s45, 18
	s_add_i32 s44, s44, s45
	s_add_i32 s44, s44, s78
	s_add_i32 s44, s44, s77
	s_add_u32 s26, s50, s44
	s_addc_u32 s27, s51, 0
	s_add_u32 s26, s26, 0x6300000
	s_addc_u32 s27, s27, 0
	global_load_dwordx4 v[64:67], v217, s[34:35] offset:0
	global_load_dwordx4 v[68:71], v217, s[34:35] offset:16
	global_load_dwordx4 v[72:75], v217, s[34:35] offset:32
	global_load_dwordx4 v[76:79], v217, s[34:35] offset:48
	global_load_dwordx4 v[0:3], v213, s[20:21] nt
	s_add_u32 s20, s20, 0x5800
	s_addc_u32 s21, s21, 0
	global_load_dwordx4 v[4:7], v213, s[20:21] nt
	s_add_u32 s20, s20, 0x5800
	s_addc_u32 s21, s21, 0
	global_load_dwordx4 v[8:11], v213, s[20:21] nt
	s_add_u32 s20, s20, 0x5800
	s_addc_u32 s21, s21, 0
	global_load_dwordx4 v[12:15], v213, s[20:21] nt
	s_add_u32 s20, s20, 0x5800
	s_addc_u32 s21, s21, 0
	global_load_dwordx4 v[16:19], v213, s[20:21] nt
	s_add_u32 s20, s20, 0x5800
	s_addc_u32 s21, s21, 0
	global_load_dwordx4 v[20:23], v213, s[20:21] nt
	s_add_u32 s20, s20, 0x5800
	s_addc_u32 s21, s21, 0
	global_load_dwordx4 v[24:27], v213, s[20:21] nt
	s_add_u32 s20, s20, 0x5800
	s_addc_u32 s21, s21, 0
	global_load_dwordx4 v[28:31], v213, s[20:21] nt
	s_add_u32 s20, s20, 0x5800
	s_addc_u32 s21, s21, 0
	global_load_dwordx4 v[32:35], v213, s[20:21] nt
	s_add_u32 s20, s20, 0x5800
	s_addc_u32 s21, s21, 0
	global_load_dwordx4 v[36:39], v213, s[20:21] nt
	s_add_u32 s20, s20, 0x5800
	s_addc_u32 s21, s21, 0
	global_load_dwordx4 v[40:43], v213, s[20:21] nt
	s_add_u32 s20, s20, 0x5800
	s_addc_u32 s21, s21, 0
	global_load_dwordx4 v[44:47], v213, s[20:21] nt
	s_add_u32 s20, s20, 0x5800
	s_addc_u32 s21, s21, 0
	global_load_dwordx4 v[48:51], v213, s[20:21] nt
	s_add_u32 s20, s20, 0x5800
	s_addc_u32 s21, s21, 0
	global_load_dwordx4 v[52:55], v213, s[20:21] nt
	s_add_u32 s20, s20, 0x5800
	s_addc_u32 s21, s21, 0
	global_load_dwordx4 v[56:59], v213, s[20:21] nt
	s_add_u32 s20, s20, 0x5800
	s_addc_u32 s21, s21, 0
	global_load_dwordx4 v[60:63], v213, s[20:21] nt
	s_waitcnt vmcnt(24)
	v_mul_f32_e32 v144, v144, v210
	v_mul_f32_e32 v145, v145, v210
	v_mul_f32_e32 v146, v146, v210
	v_mul_f32_e32 v147, v147, v210
	v_mul_f32_e32 v148, v148, v210
	v_mul_f32_e32 v149, v149, v210
	v_mul_f32_e32 v150, v150, v210
	v_mul_f32_e32 v151, v151, v210
	v_mul_f32_e32 v152, v152, v210
	v_mul_f32_e32 v153, v153, v210
	v_mul_f32_e32 v154, v154, v210
	v_mul_f32_e32 v155, v155, v210
	v_mul_f32_e32 v156, v156, v210
	v_mul_f32_e32 v157, v157, v210
	v_mul_f32_e32 v158, v158, v210
	v_mul_f32_e32 v159, v159, v210
	v_pk_mul_f32 v[80:81], v[80:81], v[144:145] op_sel_hi:[1,0]
	v_pk_mul_f32 v[82:83], v[82:83], v[144:145] op_sel_hi:[1,0]
	v_pk_mul_f32 v[84:85], v[84:85], v[144:145] op_sel:[0,1] op_sel_hi:[1,1]
	v_pk_mul_f32 v[86:87], v[86:87], v[144:145] op_sel:[0,1] op_sel_hi:[1,1]
	v_pk_mul_f32 v[88:89], v[88:89], v[146:147] op_sel_hi:[1,0]
	v_pk_mul_f32 v[90:91], v[90:91], v[146:147] op_sel_hi:[1,0]
	v_pk_mul_f32 v[92:93], v[92:93], v[146:147] op_sel:[0,1] op_sel_hi:[1,1]
	v_pk_mul_f32 v[94:95], v[94:95], v[146:147] op_sel:[0,1] op_sel_hi:[1,1]
	v_pk_mul_f32 v[96:97], v[96:97], v[148:149] op_sel_hi:[1,0]
	v_pk_mul_f32 v[98:99], v[98:99], v[148:149] op_sel_hi:[1,0]
	v_pk_mul_f32 v[100:101], v[100:101], v[148:149] op_sel:[0,1] op_sel_hi:[1,1]
	v_pk_mul_f32 v[102:103], v[102:103], v[148:149] op_sel:[0,1] op_sel_hi:[1,1]
	v_pk_mul_f32 v[104:105], v[104:105], v[150:151] op_sel_hi:[1,0]
	v_pk_mul_f32 v[106:107], v[106:107], v[150:151] op_sel_hi:[1,0]
	v_pk_mul_f32 v[108:109], v[108:109], v[150:151] op_sel:[0,1] op_sel_hi:[1,1]
	v_pk_mul_f32 v[110:111], v[110:111], v[150:151] op_sel:[0,1] op_sel_hi:[1,1]
	v_pk_mul_f32 v[112:113], v[112:113], v[152:153] op_sel_hi:[1,0]
	v_pk_mul_f32 v[114:115], v[114:115], v[152:153] op_sel_hi:[1,0]
	v_pk_mul_f32 v[116:117], v[116:117], v[152:153] op_sel:[0,1] op_sel_hi:[1,1]
	v_pk_mul_f32 v[118:119], v[118:119], v[152:153] op_sel:[0,1] op_sel_hi:[1,1]
	v_pk_mul_f32 v[120:121], v[120:121], v[154:155] op_sel_hi:[1,0]
	v_pk_mul_f32 v[122:123], v[122:123], v[154:155] op_sel_hi:[1,0]
	v_pk_mul_f32 v[124:125], v[124:125], v[154:155] op_sel:[0,1] op_sel_hi:[1,1]
	v_pk_mul_f32 v[126:127], v[126:127], v[154:155] op_sel:[0,1] op_sel_hi:[1,1]
	v_pk_mul_f32 v[128:129], v[128:129], v[156:157] op_sel_hi:[1,0]
	v_pk_mul_f32 v[130:131], v[130:131], v[156:157] op_sel_hi:[1,0]
	v_pk_mul_f32 v[132:133], v[132:133], v[156:157] op_sel:[0,1] op_sel_hi:[1,1]
	v_pk_mul_f32 v[134:135], v[134:135], v[156:157] op_sel:[0,1] op_sel_hi:[1,1]
	v_pk_mul_f32 v[136:137], v[136:137], v[158:159] op_sel_hi:[1,0]
	v_pk_mul_f32 v[138:139], v[138:139], v[158:159] op_sel_hi:[1,0]
	v_pk_mul_f32 v[140:141], v[140:141], v[158:159] op_sel:[0,1] op_sel_hi:[1,1]
	v_pk_mul_f32 v[142:143], v[142:143], v[158:159] op_sel:[0,1] op_sel_hi:[1,1]
	v_med3_f32 v80, v80, v212, v211
	v_med3_f32 v81, v81, v212, v211
	v_med3_f32 v82, v82, v212, v211
	v_med3_f32 v83, v83, v212, v211
	v_med3_f32 v84, v84, v212, v211
	v_med3_f32 v85, v85, v212, v211
	v_med3_f32 v86, v86, v212, v211
	v_med3_f32 v87, v87, v212, v211
	v_med3_f32 v88, v88, v212, v211
	v_med3_f32 v89, v89, v212, v211
	v_med3_f32 v90, v90, v212, v211
	v_med3_f32 v91, v91, v212, v211
	v_med3_f32 v92, v92, v212, v211
	v_med3_f32 v93, v93, v212, v211
	v_med3_f32 v94, v94, v212, v211
	v_med3_f32 v95, v95, v212, v211
	v_med3_f32 v96, v96, v212, v211
	v_med3_f32 v97, v97, v212, v211
	v_med3_f32 v98, v98, v212, v211
	v_med3_f32 v99, v99, v212, v211
	v_med3_f32 v100, v100, v212, v211
	v_med3_f32 v101, v101, v212, v211
	v_med3_f32 v102, v102, v212, v211
	v_med3_f32 v103, v103, v212, v211
	v_med3_f32 v104, v104, v212, v211
	v_med3_f32 v105, v105, v212, v211
	v_med3_f32 v106, v106, v212, v211
	v_med3_f32 v107, v107, v212, v211
	v_med3_f32 v108, v108, v212, v211
	v_med3_f32 v109, v109, v212, v211
	v_med3_f32 v110, v110, v212, v211
	v_med3_f32 v111, v111, v212, v211
	v_med3_f32 v112, v112, v212, v211
	v_med3_f32 v113, v113, v212, v211
	v_med3_f32 v114, v114, v212, v211
	v_med3_f32 v115, v115, v212, v211
	v_med3_f32 v116, v116, v212, v211
	v_med3_f32 v117, v117, v212, v211
	v_med3_f32 v118, v118, v212, v211
	v_med3_f32 v119, v119, v212, v211
	v_med3_f32 v120, v120, v212, v211
	v_med3_f32 v121, v121, v212, v211
	v_med3_f32 v122, v122, v212, v211
	v_med3_f32 v123, v123, v212, v211
	v_med3_f32 v124, v124, v212, v211
	v_med3_f32 v125, v125, v212, v211
	v_med3_f32 v126, v126, v212, v211
	v_med3_f32 v127, v127, v212, v211
	v_med3_f32 v128, v128, v212, v211
	v_med3_f32 v129, v129, v212, v211
	v_med3_f32 v130, v130, v212, v211
	v_med3_f32 v131, v131, v212, v211
	v_med3_f32 v132, v132, v212, v211
	v_med3_f32 v133, v133, v212, v211
	v_med3_f32 v134, v134, v212, v211
	v_med3_f32 v135, v135, v212, v211
	v_med3_f32 v136, v136, v212, v211
	v_med3_f32 v137, v137, v212, v211
	v_med3_f32 v138, v138, v212, v211
	v_med3_f32 v139, v139, v212, v211
	v_med3_f32 v140, v140, v212, v211
	v_med3_f32 v141, v141, v212, v211
	v_med3_f32 v142, v142, v212, v211
	v_med3_f32 v143, v143, v212, v211
	v_cvt_pk_fp8_f32 v160, v80, v84
	v_cvt_pk_fp8_f32 v161, v96, v100
	v_cvt_pk_fp8_f32 v162, v112, v116
	v_cvt_pk_fp8_f32 v163, v128, v132
	v_cvt_pk_fp8_f32 v164, v81, v85
	v_cvt_pk_fp8_f32 v165, v97, v101
	v_cvt_pk_fp8_f32 v166, v113, v117
	v_cvt_pk_fp8_f32 v167, v129, v133
	v_cvt_pk_fp8_f32 v168, v82, v86
	v_cvt_pk_fp8_f32 v169, v98, v102
	v_cvt_pk_fp8_f32 v170, v114, v118
	v_cvt_pk_fp8_f32 v171, v130, v134
	v_cvt_pk_fp8_f32 v172, v83, v87
	v_cvt_pk_fp8_f32 v173, v99, v103
	v_cvt_pk_fp8_f32 v174, v115, v119
	v_cvt_pk_fp8_f32 v175, v131, v135
	v_cvt_pk_fp8_f32 v160, v88, v92 op_sel:[0,0,1]
	v_cvt_pk_fp8_f32 v161, v104, v108 op_sel:[0,0,1]
	v_cvt_pk_fp8_f32 v162, v120, v124 op_sel:[0,0,1]
	v_cvt_pk_fp8_f32 v163, v136, v140 op_sel:[0,0,1]
	v_cvt_pk_fp8_f32 v164, v89, v93 op_sel:[0,0,1]
	v_cvt_pk_fp8_f32 v165, v105, v109 op_sel:[0,0,1]
	v_cvt_pk_fp8_f32 v166, v121, v125 op_sel:[0,0,1]
	v_cvt_pk_fp8_f32 v167, v137, v141 op_sel:[0,0,1]
	v_cvt_pk_fp8_f32 v168, v90, v94 op_sel:[0,0,1]
	v_cvt_pk_fp8_f32 v169, v106, v110 op_sel:[0,0,1]
	v_cvt_pk_fp8_f32 v170, v122, v126 op_sel:[0,0,1]
	v_cvt_pk_fp8_f32 v171, v138, v142 op_sel:[0,0,1]
	v_cvt_pk_fp8_f32 v172, v91, v95 op_sel:[0,0,1]
	v_cvt_pk_fp8_f32 v173, v107, v111 op_sel:[0,0,1]
	v_cvt_pk_fp8_f32 v174, v123, v127 op_sel:[0,0,1]
	v_cvt_pk_fp8_f32 v175, v139, v143 op_sel:[0,0,1]
	s_nop 0
	ds_bpermute_b32 v194, v216, v160
	ds_bpermute_b32 v195, v216, v161
	ds_bpermute_b32 v196, v216, v162
	ds_bpermute_b32 v197, v216, v163
	ds_bpermute_b32 v198, v216, v164
	ds_bpermute_b32 v199, v216, v165
	ds_bpermute_b32 v200, v216, v166
	ds_bpermute_b32 v201, v216, v167
	ds_bpermute_b32 v202, v216, v168
	ds_bpermute_b32 v203, v216, v169
	ds_bpermute_b32 v204, v216, v170
	ds_bpermute_b32 v205, v216, v171
	ds_bpermute_b32 v206, v216, v172
	ds_bpermute_b32 v207, v216, v173
	ds_bpermute_b32 v208, v216, v174
	ds_bpermute_b32 v209, v216, v175
	s_waitcnt lgkmcnt(0)
	global_store_dwordx4 v214, v[194:197], s[28:29]
	global_store_dwordx4 v214, v[198:201], s[28:29] offset:2048
	global_store_dwordx4 v215, v[202:205], s[28:29]
	global_store_dwordx4 v215, v[206:209], s[28:29] offset:2048
	s_waitcnt vmcnt(4)
	v_mul_f32_e32 v64, v64, v210
	v_mul_f32_e32 v65, v65, v210
	v_mul_f32_e32 v66, v66, v210
	v_mul_f32_e32 v67, v67, v210
	v_mul_f32_e32 v68, v68, v210
	v_mul_f32_e32 v69, v69, v210
	v_mul_f32_e32 v70, v70, v210
	v_mul_f32_e32 v71, v71, v210
	v_mul_f32_e32 v72, v72, v210
	v_mul_f32_e32 v73, v73, v210
	v_mul_f32_e32 v74, v74, v210
	v_mul_f32_e32 v75, v75, v210
	v_mul_f32_e32 v76, v76, v210
	v_mul_f32_e32 v77, v77, v210
	v_mul_f32_e32 v78, v78, v210
	v_mul_f32_e32 v79, v79, v210
	v_pk_mul_f32 v[0:1], v[0:1], v[64:65] op_sel_hi:[1,0]
	v_pk_mul_f32 v[2:3], v[2:3], v[64:65] op_sel_hi:[1,0]
	v_pk_mul_f32 v[4:5], v[4:5], v[64:65] op_sel:[0,1] op_sel_hi:[1,1]
	v_pk_mul_f32 v[6:7], v[6:7], v[64:65] op_sel:[0,1] op_sel_hi:[1,1]
	v_pk_mul_f32 v[8:9], v[8:9], v[66:67] op_sel_hi:[1,0]
	v_pk_mul_f32 v[10:11], v[10:11], v[66:67] op_sel_hi:[1,0]
	v_pk_mul_f32 v[12:13], v[12:13], v[66:67] op_sel:[0,1] op_sel_hi:[1,1]
	v_pk_mul_f32 v[14:15], v[14:15], v[66:67] op_sel:[0,1] op_sel_hi:[1,1]
	v_pk_mul_f32 v[16:17], v[16:17], v[68:69] op_sel_hi:[1,0]
	v_pk_mul_f32 v[18:19], v[18:19], v[68:69] op_sel_hi:[1,0]
	v_pk_mul_f32 v[20:21], v[20:21], v[68:69] op_sel:[0,1] op_sel_hi:[1,1]
	v_pk_mul_f32 v[22:23], v[22:23], v[68:69] op_sel:[0,1] op_sel_hi:[1,1]
	v_pk_mul_f32 v[24:25], v[24:25], v[70:71] op_sel_hi:[1,0]
	v_pk_mul_f32 v[26:27], v[26:27], v[70:71] op_sel_hi:[1,0]
	v_pk_mul_f32 v[28:29], v[28:29], v[70:71] op_sel:[0,1] op_sel_hi:[1,1]
	v_pk_mul_f32 v[30:31], v[30:31], v[70:71] op_sel:[0,1] op_sel_hi:[1,1]
	v_pk_mul_f32 v[32:33], v[32:33], v[72:73] op_sel_hi:[1,0]
	v_pk_mul_f32 v[34:35], v[34:35], v[72:73] op_sel_hi:[1,0]
	v_pk_mul_f32 v[36:37], v[36:37], v[72:73] op_sel:[0,1] op_sel_hi:[1,1]
	v_pk_mul_f32 v[38:39], v[38:39], v[72:73] op_sel:[0,1] op_sel_hi:[1,1]
	v_pk_mul_f32 v[40:41], v[40:41], v[74:75] op_sel_hi:[1,0]
	v_pk_mul_f32 v[42:43], v[42:43], v[74:75] op_sel_hi:[1,0]
	v_pk_mul_f32 v[44:45], v[44:45], v[74:75] op_sel:[0,1] op_sel_hi:[1,1]
	v_pk_mul_f32 v[46:47], v[46:47], v[74:75] op_sel:[0,1] op_sel_hi:[1,1]
	v_pk_mul_f32 v[48:49], v[48:49], v[76:77] op_sel_hi:[1,0]
	v_pk_mul_f32 v[50:51], v[50:51], v[76:77] op_sel_hi:[1,0]
	v_pk_mul_f32 v[52:53], v[52:53], v[76:77] op_sel:[0,1] op_sel_hi:[1,1]
	v_pk_mul_f32 v[54:55], v[54:55], v[76:77] op_sel:[0,1] op_sel_hi:[1,1]
	v_pk_mul_f32 v[56:57], v[56:57], v[78:79] op_sel_hi:[1,0]
	v_pk_mul_f32 v[58:59], v[58:59], v[78:79] op_sel_hi:[1,0]
	v_pk_mul_f32 v[60:61], v[60:61], v[78:79] op_sel:[0,1] op_sel_hi:[1,1]
	v_pk_mul_f32 v[62:63], v[62:63], v[78:79] op_sel:[0,1] op_sel_hi:[1,1]
	v_med3_f32 v0, v0, v212, v211
	v_med3_f32 v1, v1, v212, v211
	v_med3_f32 v2, v2, v212, v211
	v_med3_f32 v3, v3, v212, v211
	v_med3_f32 v4, v4, v212, v211
	v_med3_f32 v5, v5, v212, v211
	v_med3_f32 v6, v6, v212, v211
	v_med3_f32 v7, v7, v212, v211
	v_med3_f32 v8, v8, v212, v211
	v_med3_f32 v9, v9, v212, v211
	v_med3_f32 v10, v10, v212, v211
	v_med3_f32 v11, v11, v212, v211
	v_med3_f32 v12, v12, v212, v211
	v_med3_f32 v13, v13, v212, v211
	v_med3_f32 v14, v14, v212, v211
	v_med3_f32 v15, v15, v212, v211
	v_med3_f32 v16, v16, v212, v211
	v_med3_f32 v17, v17, v212, v211
	v_med3_f32 v18, v18, v212, v211
	v_med3_f32 v19, v19, v212, v211
	v_med3_f32 v20, v20, v212, v211
	v_med3_f32 v21, v21, v212, v211
	v_med3_f32 v22, v22, v212, v211
	v_med3_f32 v23, v23, v212, v211
	v_med3_f32 v24, v24, v212, v211
	v_med3_f32 v25, v25, v212, v211
	v_med3_f32 v26, v26, v212, v211
	v_med3_f32 v27, v27, v212, v211
	v_med3_f32 v28, v28, v212, v211
	v_med3_f32 v29, v29, v212, v211
	v_med3_f32 v30, v30, v212, v211
	v_med3_f32 v31, v31, v212, v211
	v_med3_f32 v32, v32, v212, v211
	v_med3_f32 v33, v33, v212, v211
	v_med3_f32 v34, v34, v212, v211
	v_med3_f32 v35, v35, v212, v211
	v_med3_f32 v36, v36, v212, v211
	v_med3_f32 v37, v37, v212, v211
	v_med3_f32 v38, v38, v212, v211
	v_med3_f32 v39, v39, v212, v211
	v_med3_f32 v40, v40, v212, v211
	v_med3_f32 v41, v41, v212, v211
	v_med3_f32 v42, v42, v212, v211
	v_med3_f32 v43, v43, v212, v211
	v_med3_f32 v44, v44, v212, v211
	v_med3_f32 v45, v45, v212, v211
	v_med3_f32 v46, v46, v212, v211
	v_med3_f32 v47, v47, v212, v211
	v_med3_f32 v48, v48, v212, v211
	v_med3_f32 v49, v49, v212, v211
	v_med3_f32 v50, v50, v212, v211
	v_med3_f32 v51, v51, v212, v211
	v_med3_f32 v52, v52, v212, v211
	v_med3_f32 v53, v53, v212, v211
	v_med3_f32 v54, v54, v212, v211
	v_med3_f32 v55, v55, v212, v211
	v_med3_f32 v56, v56, v212, v211
	v_med3_f32 v57, v57, v212, v211
	v_med3_f32 v58, v58, v212, v211
	v_med3_f32 v59, v59, v212, v211
	v_med3_f32 v60, v60, v212, v211
	v_med3_f32 v61, v61, v212, v211
	v_med3_f32 v62, v62, v212, v211
	v_med3_f32 v63, v63, v212, v211
	v_cvt_pk_fp8_f32 v160, v0, v4
	v_cvt_pk_fp8_f32 v161, v16, v20
	v_cvt_pk_fp8_f32 v162, v32, v36
	v_cvt_pk_fp8_f32 v163, v48, v52
	v_cvt_pk_fp8_f32 v164, v1, v5
	v_cvt_pk_fp8_f32 v165, v17, v21
	v_cvt_pk_fp8_f32 v166, v33, v37
	v_cvt_pk_fp8_f32 v167, v49, v53
	v_cvt_pk_fp8_f32 v168, v2, v6
	v_cvt_pk_fp8_f32 v169, v18, v22
	v_cvt_pk_fp8_f32 v170, v34, v38
	v_cvt_pk_fp8_f32 v171, v50, v54
	v_cvt_pk_fp8_f32 v172, v3, v7
	v_cvt_pk_fp8_f32 v173, v19, v23
	v_cvt_pk_fp8_f32 v174, v35, v39
	v_cvt_pk_fp8_f32 v175, v51, v55
	v_cvt_pk_fp8_f32 v160, v8, v12 op_sel:[0,0,1]
	v_cvt_pk_fp8_f32 v161, v24, v28 op_sel:[0,0,1]
	v_cvt_pk_fp8_f32 v162, v40, v44 op_sel:[0,0,1]
	v_cvt_pk_fp8_f32 v163, v56, v60 op_sel:[0,0,1]
	v_cvt_pk_fp8_f32 v164, v9, v13 op_sel:[0,0,1]
	v_cvt_pk_fp8_f32 v165, v25, v29 op_sel:[0,0,1]
	v_cvt_pk_fp8_f32 v166, v41, v45 op_sel:[0,0,1]
	v_cvt_pk_fp8_f32 v167, v57, v61 op_sel:[0,0,1]
	v_cvt_pk_fp8_f32 v168, v10, v14 op_sel:[0,0,1]
	v_cvt_pk_fp8_f32 v169, v26, v30 op_sel:[0,0,1]
	v_cvt_pk_fp8_f32 v170, v42, v46 op_sel:[0,0,1]
	v_cvt_pk_fp8_f32 v171, v58, v62 op_sel:[0,0,1]
	v_cvt_pk_fp8_f32 v172, v11, v15 op_sel:[0,0,1]
	v_cvt_pk_fp8_f32 v173, v27, v31 op_sel:[0,0,1]
	v_cvt_pk_fp8_f32 v174, v43, v47 op_sel:[0,0,1]
	v_cvt_pk_fp8_f32 v175, v59, v63 op_sel:[0,0,1]
	s_nop 0
	ds_bpermute_b32 v194, v216, v160
	ds_bpermute_b32 v195, v216, v161
	ds_bpermute_b32 v196, v216, v162
	ds_bpermute_b32 v197, v216, v163
	ds_bpermute_b32 v198, v216, v164
	ds_bpermute_b32 v199, v216, v165
	ds_bpermute_b32 v200, v216, v166
	ds_bpermute_b32 v201, v216, v167
	ds_bpermute_b32 v202, v216, v168
	ds_bpermute_b32 v203, v216, v169
	ds_bpermute_b32 v204, v216, v170
	ds_bpermute_b32 v205, v216, v171
	ds_bpermute_b32 v206, v216, v172
	ds_bpermute_b32 v207, v216, v173
	ds_bpermute_b32 v208, v216, v174
	ds_bpermute_b32 v209, v216, v175
	s_waitcnt lgkmcnt(0)
	global_store_dwordx4 v214, v[194:197], s[26:27]
	global_store_dwordx4 v214, v[198:201], s[26:27] offset:2048
	global_store_dwordx4 v215, v[202:205], s[26:27]
	global_store_dwordx4 v215, v[206:209], s[26:27] offset:2048
	s_branch .Lcp_p4_done
.Lcp_p4_two:
	s_waitcnt vmcnt(4)
	v_mul_f32_e32 v144, v144, v210
	v_mul_f32_e32 v145, v145, v210
	v_mul_f32_e32 v146, v146, v210
	v_mul_f32_e32 v147, v147, v210
	v_mul_f32_e32 v148, v148, v210
	v_mul_f32_e32 v149, v149, v210
	v_mul_f32_e32 v150, v150, v210
	v_mul_f32_e32 v151, v151, v210
	v_mul_f32_e32 v152, v152, v210
	v_mul_f32_e32 v153, v153, v210
	v_mul_f32_e32 v154, v154, v210
	v_mul_f32_e32 v155, v155, v210
	v_mul_f32_e32 v156, v156, v210
	v_mul_f32_e32 v157, v157, v210
	v_mul_f32_e32 v158, v158, v210
	v_mul_f32_e32 v159, v159, v210
	v_pk_mul_f32 v[80:81], v[80:81], v[144:145] op_sel_hi:[1,0]
	v_pk_mul_f32 v[82:83], v[82:83], v[144:145] op_sel_hi:[1,0]
	v_pk_mul_f32 v[84:85], v[84:85], v[144:145] op_sel:[0,1] op_sel_hi:[1,1]
	v_pk_mul_f32 v[86:87], v[86:87], v[144:145] op_sel:[0,1] op_sel_hi:[1,1]
	v_pk_mul_f32 v[88:89], v[88:89], v[146:147] op_sel_hi:[1,0]
	v_pk_mul_f32 v[90:91], v[90:91], v[146:147] op_sel_hi:[1,0]
	v_pk_mul_f32 v[92:93], v[92:93], v[146:147] op_sel:[0,1] op_sel_hi:[1,1]
	v_pk_mul_f32 v[94:95], v[94:95], v[146:147] op_sel:[0,1] op_sel_hi:[1,1]
	v_pk_mul_f32 v[96:97], v[96:97], v[148:149] op_sel_hi:[1,0]
	v_pk_mul_f32 v[98:99], v[98:99], v[148:149] op_sel_hi:[1,0]
	v_pk_mul_f32 v[100:101], v[100:101], v[148:149] op_sel:[0,1] op_sel_hi:[1,1]
	v_pk_mul_f32 v[102:103], v[102:103], v[148:149] op_sel:[0,1] op_sel_hi:[1,1]
	v_pk_mul_f32 v[104:105], v[104:105], v[150:151] op_sel_hi:[1,0]
	v_pk_mul_f32 v[106:107], v[106:107], v[150:151] op_sel_hi:[1,0]
	v_pk_mul_f32 v[108:109], v[108:109], v[150:151] op_sel:[0,1] op_sel_hi:[1,1]
	v_pk_mul_f32 v[110:111], v[110:111], v[150:151] op_sel:[0,1] op_sel_hi:[1,1]
	v_pk_mul_f32 v[112:113], v[112:113], v[152:153] op_sel_hi:[1,0]
	v_pk_mul_f32 v[114:115], v[114:115], v[152:153] op_sel_hi:[1,0]
	v_pk_mul_f32 v[116:117], v[116:117], v[152:153] op_sel:[0,1] op_sel_hi:[1,1]
	v_pk_mul_f32 v[118:119], v[118:119], v[152:153] op_sel:[0,1] op_sel_hi:[1,1]
	v_pk_mul_f32 v[120:121], v[120:121], v[154:155] op_sel_hi:[1,0]
	v_pk_mul_f32 v[122:123], v[122:123], v[154:155] op_sel_hi:[1,0]
	v_pk_mul_f32 v[124:125], v[124:125], v[154:155] op_sel:[0,1] op_sel_hi:[1,1]
	v_pk_mul_f32 v[126:127], v[126:127], v[154:155] op_sel:[0,1] op_sel_hi:[1,1]
	v_pk_mul_f32 v[128:129], v[128:129], v[156:157] op_sel_hi:[1,0]
	v_pk_mul_f32 v[130:131], v[130:131], v[156:157] op_sel_hi:[1,0]
	v_pk_mul_f32 v[132:133], v[132:133], v[156:157] op_sel:[0,1] op_sel_hi:[1,1]
	v_pk_mul_f32 v[134:135], v[134:135], v[156:157] op_sel:[0,1] op_sel_hi:[1,1]
	v_pk_mul_f32 v[136:137], v[136:137], v[158:159] op_sel_hi:[1,0]
	v_pk_mul_f32 v[138:139], v[138:139], v[158:159] op_sel_hi:[1,0]
	v_pk_mul_f32 v[140:141], v[140:141], v[158:159] op_sel:[0,1] op_sel_hi:[1,1]
	v_pk_mul_f32 v[142:143], v[142:143], v[158:159] op_sel:[0,1] op_sel_hi:[1,1]
	v_med3_f32 v80, v80, v212, v211
	v_med3_f32 v81, v81, v212, v211
	v_med3_f32 v82, v82, v212, v211
	v_med3_f32 v83, v83, v212, v211
	v_med3_f32 v84, v84, v212, v211
	v_med3_f32 v85, v85, v212, v211
	v_med3_f32 v86, v86, v212, v211
	v_med3_f32 v87, v87, v212, v211
	v_med3_f32 v88, v88, v212, v211
	v_med3_f32 v89, v89, v212, v211
	v_med3_f32 v90, v90, v212, v211
	v_med3_f32 v91, v91, v212, v211
	v_med3_f32 v92, v92, v212, v211
	v_med3_f32 v93, v93, v212, v211
	v_med3_f32 v94, v94, v212, v211
	v_med3_f32 v95, v95, v212, v211
	v_med3_f32 v96, v96, v212, v211
	v_med3_f32 v97, v97, v212, v211
	v_med3_f32 v98, v98, v212, v211
	v_med3_f32 v99, v99, v212, v211
	v_med3_f32 v100, v100, v212, v211
	v_med3_f32 v101, v101, v212, v211
	v_med3_f32 v102, v102, v212, v211
	v_med3_f32 v103, v103, v212, v211
	v_med3_f32 v104, v104, v212, v211
	v_med3_f32 v105, v105, v212, v211
	v_med3_f32 v106, v106, v212, v211
	v_med3_f32 v107, v107, v212, v211
	v_med3_f32 v108, v108, v212, v211
	v_med3_f32 v109, v109, v212, v211
	v_med3_f32 v110, v110, v212, v211
	v_med3_f32 v111, v111, v212, v211
	v_med3_f32 v112, v112, v212, v211
	v_med3_f32 v113, v113, v212, v211
	v_med3_f32 v114, v114, v212, v211
	v_med3_f32 v115, v115, v212, v211
	v_med3_f32 v116, v116, v212, v211
	v_med3_f32 v117, v117, v212, v211
	v_med3_f32 v118, v118, v212, v211
	v_med3_f32 v119, v119, v212, v211
	v_med3_f32 v120, v120, v212, v211
	v_med3_f32 v121, v121, v212, v211
	v_med3_f32 v122, v122, v212, v211
	v_med3_f32 v123, v123, v212, v211
	v_med3_f32 v124, v124, v212, v211
	v_med3_f32 v125, v125, v212, v211
	v_med3_f32 v126, v126, v212, v211
	v_med3_f32 v127, v127, v212, v211
	v_med3_f32 v128, v128, v212, v211
	v_med3_f32 v129, v129, v212, v211
	v_med3_f32 v130, v130, v212, v211
	v_med3_f32 v131, v131, v212, v211
	v_med3_f32 v132, v132, v212, v211
	v_med3_f32 v133, v133, v212, v211
	v_med3_f32 v134, v134, v212, v211
	v_med3_f32 v135, v135, v212, v211
	v_med3_f32 v136, v136, v212, v211
	v_med3_f32 v137, v137, v212, v211
	v_med3_f32 v138, v138, v212, v211
	v_med3_f32 v139, v139, v212, v211
	v_med3_f32 v140, v140, v212, v211
	v_med3_f32 v141, v141, v212, v211
	v_med3_f32 v142, v142, v212, v211
	v_med3_f32 v143, v143, v212, v211
	v_cvt_pk_fp8_f32 v160, v80, v84
	v_cvt_pk_fp8_f32 v161, v96, v100
	v_cvt_pk_fp8_f32 v162, v112, v116
	v_cvt_pk_fp8_f32 v163, v128, v132
	v_cvt_pk_fp8_f32 v164, v81, v85
	v_cvt_pk_fp8_f32 v165, v97, v101
	v_cvt_pk_fp8_f32 v166, v113, v117
	v_cvt_pk_fp8_f32 v167, v129, v133
	v_cvt_pk_fp8_f32 v168, v82, v86
	v_cvt_pk_fp8_f32 v169, v98, v102
	v_cvt_pk_fp8_f32 v170, v114, v118
	v_cvt_pk_fp8_f32 v171, v130, v134
	v_cvt_pk_fp8_f32 v172, v83, v87
	v_cvt_pk_fp8_f32 v173, v99, v103
	v_cvt_pk_fp8_f32 v174, v115, v119
	v_cvt_pk_fp8_f32 v175, v131, v135
	v_cvt_pk_fp8_f32 v160, v88, v92 op_sel:[0,0,1]
	v_cvt_pk_fp8_f32 v161, v104, v108 op_sel:[0,0,1]
	v_cvt_pk_fp8_f32 v162, v120, v124 op_sel:[0,0,1]
	v_cvt_pk_fp8_f32 v163, v136, v140 op_sel:[0,0,1]
	v_cvt_pk_fp8_f32 v164, v89, v93 op_sel:[0,0,1]
	v_cvt_pk_fp8_f32 v165, v105, v109 op_sel:[0,0,1]
	v_cvt_pk_fp8_f32 v166, v121, v125 op_sel:[0,0,1]
	v_cvt_pk_fp8_f32 v167, v137, v141 op_sel:[0,0,1]
	v_cvt_pk_fp8_f32 v168, v90, v94 op_sel:[0,0,1]
	v_cvt_pk_fp8_f32 v169, v106, v110 op_sel:[0,0,1]
	v_cvt_pk_fp8_f32 v170, v122, v126 op_sel:[0,0,1]
	v_cvt_pk_fp8_f32 v171, v138, v142 op_sel:[0,0,1]
	v_cvt_pk_fp8_f32 v172, v91, v95 op_sel:[0,0,1]
	v_cvt_pk_fp8_f32 v173, v107, v111 op_sel:[0,0,1]
	v_cvt_pk_fp8_f32 v174, v123, v127 op_sel:[0,0,1]
	v_cvt_pk_fp8_f32 v175, v139, v143 op_sel:[0,0,1]
	s_nop 0
	ds_bpermute_b32 v194, v216, v160
	ds_bpermute_b32 v195, v216, v161
	ds_bpermute_b32 v196, v216, v162
	ds_bpermute_b32 v197, v216, v163
	ds_bpermute_b32 v198, v216, v164
	ds_bpermute_b32 v199, v216, v165
	ds_bpermute_b32 v200, v216, v166
	ds_bpermute_b32 v201, v216, v167
	ds_bpermute_b32 v202, v216, v168
	ds_bpermute_b32 v203, v216, v169
	ds_bpermute_b32 v204, v216, v170
	ds_bpermute_b32 v205, v216, v171
	ds_bpermute_b32 v206, v216, v172
	ds_bpermute_b32 v207, v216, v173
	ds_bpermute_b32 v208, v216, v174
	ds_bpermute_b32 v209, v216, v175
	s_waitcnt lgkmcnt(0)
	global_store_dwordx4 v214, v[194:197], s[28:29]
	global_store_dwordx4 v214, v[198:201], s[28:29] offset:2048
	global_store_dwordx4 v215, v[202:205], s[28:29]
	global_store_dwordx4 v215, v[206:209], s[28:29] offset:2048
